# layer-0 modnorm (phases 1 and 7 share one compiled body): replaced by two specialised pipelined instances (gain loaded once, rows k+1/k+2 in flight) selected on the phase index
# speedup vs baseline: 1.0070x; 1.0049x over previous
; DEV unsigned cvt_pk_bf16(float lo, float hi) { unsigned r; asm volatile("v_cvt_pk_bf16_f32 %0, %1, %2" : "=v"(r) : "v"(lo), "v"(hi)); return r; }
; DEV void modnorm_rows(const float* srcX, const float* srcC, int nrows, const float* g, const float* shift, const float* scale, bf16_t* dst, int gw, int NGW, int lane) {
;     for (int row0 = gw; row0 < nrows; row0 += 2 * NGW) {
;         const int row1 = row0 + NGW; const bool has1 = row1 < nrows;
;         const float* xr0 = (row0 < TX) ? srcX + (size_t)row0 * DM : srcC + (size_t)(row0 - TX) * DM;
;         const float* xr1 = !has1 ? xr0 : ((row1 < TX) ? srcX + (size_t)row1 * DM : srcC + (size_t)(row1 - TX) * DM);
;         f32x4 v0[4], v1[4]; float s0 = 0.f, s1 = 0.f;
; #pragma unroll
;         for (int j = 0; j < 4; ++j) { v0[j] = __builtin_nontemporal_load((const f32x4*)(xr0 + 256 * j + 4 * lane)); v1[j] = __builtin_nontemporal_load((const f32x4*)(xr1 + 256 * j + 4 * lane)); }
; #pragma unroll
;         for (int j = 0; j < 4; ++j) { s0 += (v0[j][0] * v0[j][0] + v0[j][1] * v0[j][1]) + (v0[j][2] * v0[j][2] + v0[j][3] * v0[j][3]); s1 += (v1[j][0] * v1[j][0] + v1[j][1] * v1[j][1]) + (v1[j][2] * v1[j][2] + v1[j][3] * v1[j][3]); }
;         const float rstd0 = 1.0f / sqrtf(wave_sum(s0) * (1.f / DM) + EPS), rstd1 = 1.0f / sqrtf(wave_sum(s1) * (1.f / DM) + EPS);
;         const int mr0 = (row0 < TX) ? (row0 >> 12) : 8, mr1 = (row1 < TX) ? (row1 >> 12) : 8;
; #pragma unroll
;         for (int j = 0; j < 4; ++j) { const int col = 256 * j + 4 * lane; const f32x4 gg = *(const f32x4*)(g + col);
;             { const f32x4 sh = *(const f32x4*)(shift + (size_t)mr0 * 6144 + col), sc = *(const f32x4*)(scale + (size_t)mr0 * 6144 + col); f32x4 y;
; #pragma unroll
;                 for (int e = 0; e < 4; ++e) y[e] = (v0[j][e] * rstd0 * gg[e]) * (1.f + sc[e]) + sh[e];
;                 u32x2 w; w.x = cvt_pk_bf16(y[0], y[1]); w.y = cvt_pk_bf16(y[2], y[3]); *(u32x2*)(dst + (size_t)row0 * DM + col) = w; }
;             if (has1) { const f32x4 sh = *(const f32x4*)(shift + (size_t)mr1 * 6144 + col), sc = *(const f32x4*)(scale + (size_t)mr1 * 6144 + col); f32x4 y;
; #pragma unroll
;                 for (int e = 0; e < 4; ++e) y[e] = (v1[j][e] * rstd1 * gg[e]) * (1.f + sc[e]) + sh[e];
;                 u32x2 w; w.x = cvt_pk_bf16(y[0], y[1]); w.y = cvt_pk_bf16(y[2], y[3]); *(u32x2*)(dst + (size_t)row1 * DM + col) = w; } }
.LBB0_1342:
.LBB0_1343:
	s_andn2_b64 vcc, exec, s[0:1]
	s_cbranch_vccnz .LBB0_1358
	s_cmp_gt_i32 s14, 0x87ff
	s_cbranch_scc1 .LBB0_1358
	s_cmp_eq_u32 s77, 1
	s_cbranch_scc1 .Lmn_phase1
	s_waitcnt vmcnt(0) lgkmcnt(0)
	v_readlane_b32 s2, v251, 2
	v_readlane_b32 s3, v251, 3
	v_readlane_b32 s1, v251, 1
	v_readlane_b32 s14, v251, 0
	v_readlane_b32 s20, v251, 4
	v_mbcnt_lo_u32_b32 v122, -1, 0
	v_mbcnt_hi_u32_b32 v122, -1, v122
	s_load_dwordx2 s[12:13], s[2:3], 0x110
	s_load_dwordx2 s[16:17], s[2:3], 0x28
	s_lshl_b32 s1, s1, 3
	s_lshl_b32 s14, s14, 3
	s_lshr_b32 s20, s20, 6
	s_add_u32 s14, s14, s20
	s_mov_b32 s15, s14
	v_lshlrev_b32_e32 v123, 3, v122
	v_lshlrev_b32_e32 v122, 4, v122
	v_mov_b32_e32 v140, 0x358637bd
	v_mov_b32_e32 v141, 0x260
	s_waitcnt lgkmcnt(0)
	global_load_dwordx4 v[98:101], v122, s[16:17] offset:0
	global_load_dwordx4 v[102:105], v122, s[16:17] offset:1024
	global_load_dwordx4 v[106:109], v122, s[16:17] offset:2048
	global_load_dwordx4 v[110:113], v122, s[16:17] offset:3072
	s_add_u32 s4, s12, 0x1c00000
	s_addc_u32 s5, s13, 0
	s_add_u32 s6, s4, 0x8000000
	s_addc_u32 s7, s5, 0
	s_add_u32 s8, s12, 0x3000
	s_addc_u32 s9, s13, 0
	s_add_u32 s10, s12, 0x4000
	s_addc_u32 s11, s13, 0
	s_add_u32 s12, s12, 0xa400000
	s_addc_u32 s13, s13, 0
	s_cmp_ge_i32 s14, 0x8800
	s_cbranch_scc1 .Lmn7_ni_2
	s_sub_i32 s0, s14, 0x8000
	s_lshr_b32 s20, s14, 12
	s_cmp_lt_i32 s14, 0x8000
	s_cselect_b32 s0, s14, s0
	s_cselect_b32 s20, s20, 8
	s_cselect_b32 s16, s4, s6
	s_cselect_b32 s17, s5, s7
	s_lshl_b32 s0, s0, 12
	s_mul_i32 s20, s20, 0x6000
	s_add_u32 s16, s16, s0
	s_addc_u32 s17, s17, 0
	s_add_u32 s18, s8, s20
	s_addc_u32 s19, s9, 0
	global_load_dwordx4 v[2:5], v122, s[16:17] offset:0 nt
	global_load_dwordx4 v[6:9], v122, s[16:17] offset:1024 nt
	global_load_dwordx4 v[10:13], v122, s[16:17] offset:2048 nt
	global_load_dwordx4 v[14:17], v122, s[16:17] offset:3072 nt
	global_load_dwordx4 v[18:21], v122, s[18:19] offset:0
	global_load_dwordx4 v[22:25], v122, s[18:19] offset:1024
	global_load_dwordx4 v[26:29], v122, s[18:19] offset:2048
	global_load_dwordx4 v[30:33], v122, s[18:19] offset:3072
	s_add_u32 s18, s10, s20
	s_addc_u32 s19, s11, 0
	global_load_dwordx4 v[34:37], v122, s[18:19] offset:0
	global_load_dwordx4 v[38:41], v122, s[18:19] offset:1024
	global_load_dwordx4 v[42:45], v122, s[18:19] offset:2048
	global_load_dwordx4 v[46:49], v122, s[18:19] offset:3072
.Lmn7_ni_2:
	s_add_u32 s14, s14, s1
	s_cmp_ge_i32 s14, 0x8800
	s_cbranch_scc1 .Lmn7_ni_3
	s_sub_i32 s0, s14, 0x8000
	s_lshr_b32 s20, s14, 12
	s_cmp_lt_i32 s14, 0x8000
	s_cselect_b32 s0, s14, s0
	s_cselect_b32 s20, s20, 8
	s_cselect_b32 s16, s4, s6
	s_cselect_b32 s17, s5, s7
	s_lshl_b32 s0, s0, 12
	s_mul_i32 s20, s20, 0x6000
	s_add_u32 s16, s16, s0
	s_addc_u32 s17, s17, 0
	s_add_u32 s18, s8, s20
	s_addc_u32 s19, s9, 0
	global_load_dwordx4 v[50:53], v122, s[16:17] offset:0 nt
	global_load_dwordx4 v[54:57], v122, s[16:17] offset:1024 nt
	global_load_dwordx4 v[58:61], v122, s[16:17] offset:2048 nt
	global_load_dwordx4 v[62:65], v122, s[16:17] offset:3072 nt
	global_load_dwordx4 v[66:69], v122, s[18:19] offset:0
	global_load_dwordx4 v[70:73], v122, s[18:19] offset:1024
	global_load_dwordx4 v[74:77], v122, s[18:19] offset:2048
	global_load_dwordx4 v[78:81], v122, s[18:19] offset:3072
	s_add_u32 s18, s10, s20
	s_addc_u32 s19, s11, 0
	global_load_dwordx4 v[82:85], v122, s[18:19] offset:0
	global_load_dwordx4 v[86:89], v122, s[18:19] offset:1024
	global_load_dwordx4 v[90:93], v122, s[18:19] offset:2048
	global_load_dwordx4 v[94:97], v122, s[18:19] offset:3072

; DEV unsigned cvt_pk_bf16(float lo, float hi) { unsigned r; asm volatile("v_cvt_pk_bf16_f32 %0, %1, %2" : "=v"(r) : "v"(lo), "v"(hi)); return r; }
; DEV void modnorm_rows(const float* srcX, const float* srcC, int nrows, const float* g, const float* shift, const float* scale, bf16_t* dst, int gw, int NGW, int lane) {
;     for (int row0 = gw; row0 < nrows; row0 += 2 * NGW) {
;         const int row1 = row0 + NGW; const bool has1 = row1 < nrows;
;         const float* xr0 = (row0 < TX) ? srcX + (size_t)row0 * DM : srcC + (size_t)(row0 - TX) * DM;
;         const float* xr1 = !has1 ? xr0 : ((row1 < TX) ? srcX + (size_t)row1 * DM : srcC + (size_t)(row1 - TX) * DM);
;         f32x4 v0[4], v1[4]; float s0 = 0.f, s1 = 0.f;
; #pragma unroll
;         for (int j = 0; j < 4; ++j) { v0[j] = __builtin_nontemporal_load((const f32x4*)(xr0 + 256 * j + 4 * lane)); v1[j] = __builtin_nontemporal_load((const f32x4*)(xr1 + 256 * j + 4 * lane)); }
; #pragma unroll
;         for (int j = 0; j < 4; ++j) { s0 += (v0[j][0] * v0[j][0] + v0[j][1] * v0[j][1]) + (v0[j][2] * v0[j][2] + v0[j][3] * v0[j][3]); s1 += (v1[j][0] * v1[j][0] + v1[j][1] * v1[j][1]) + (v1[j][2] * v1[j][2] + v1[j][3] * v1[j][3]); }
;         const float rstd0 = 1.0f / sqrtf(wave_sum(s0) * (1.f / DM) + EPS), rstd1 = 1.0f / sqrtf(wave_sum(s1) * (1.f / DM) + EPS);
;         const int mr0 = (row0 < TX) ? (row0 >> 12) : 8, mr1 = (row1 < TX) ? (row1 >> 12) : 8;
; #pragma unroll
;         for (int j = 0; j < 4; ++j) { const int col = 256 * j + 4 * lane; const f32x4 gg = *(const f32x4*)(g + col);
;             { const f32x4 sh = *(const f32x4*)(shift + (size_t)mr0 * 6144 + col), sc = *(const f32x4*)(scale + (size_t)mr0 * 6144 + col); f32x4 y;
; #pragma unroll
;                 for (int e = 0; e < 4; ++e) y[e] = (v0[j][e] * rstd0 * gg[e]) * (1.f + sc[e]) + sh[e];
;                 u32x2 w; w.x = cvt_pk_bf16(y[0], y[1]); w.y = cvt_pk_bf16(y[2], y[3]); *(u32x2*)(dst + (size_t)row0 * DM + col) = w; }
;             if (has1) { const f32x4 sh = *(const f32x4*)(shift + (size_t)mr1 * 6144 + col), sc = *(const f32x4*)(scale + (size_t)mr1 * 6144 + col); f32x4 y;
; #pragma unroll
;                 for (int e = 0; e < 4; ++e) y[e] = (v1[j][e] * rstd1 * gg[e]) * (1.f + sc[e]) + sh[e];
;                 u32x2 w; w.x = cvt_pk_bf16(y[0], y[1]); w.y = cvt_pk_bf16(y[2], y[3]); *(u32x2*)(dst + (size_t)row1 * DM + col) = w; } }
.Lmn7_wj_5:
	v_mul_f32_e32 v114, v3, v3
	v_mul_f32_e32 v115, v5, v5
	v_mul_f32_e32 v116, v7, v7
	v_mul_f32_e32 v117, v9, v9
	v_mul_f32_e32 v118, v11, v11
	v_mul_f32_e32 v119, v13, v13
	v_mul_f32_e32 v120, v15, v15
	v_mul_f32_e32 v121, v17, v17
	v_fmac_f32_e32 v114, v2, v2
	v_fmac_f32_e32 v115, v4, v4
	v_fmac_f32_e32 v116, v6, v6
	v_fmac_f32_e32 v117, v8, v8
	v_fmac_f32_e32 v118, v10, v10
	v_fmac_f32_e32 v119, v12, v12
	v_fmac_f32_e32 v120, v14, v14
	v_fmac_f32_e32 v121, v16, v16
	v_add_f32_e32 v114, v114, v115
	v_add_f32_e32 v116, v116, v117
	v_add_f32_e32 v118, v118, v119
	v_add_f32_e32 v120, v120, v121
	v_add_f32_e32 v124, v114, v116
	v_add_f32_e32 v124, v124, v118
	v_add_f32_e32 v124, v124, v120
	v_add_f32_e32 v34, 1.0, v34
	v_add_f32_e32 v35, 1.0, v35
	v_add_f32_dpp v124, v124, v124 quad_perm:[1,0,3,2] row_mask:0xf bank_mask:0xf
	v_add_f32_e32 v36, 1.0, v36
	v_add_f32_e32 v37, 1.0, v37
	v_add_f32_dpp v124, v124, v124 quad_perm:[2,3,0,1] row_mask:0xf bank_mask:0xf
	v_add_f32_e32 v38, 1.0, v38
	v_add_f32_e32 v39, 1.0, v39
	v_add_f32_dpp v124, v124, v124 row_half_mirror row_mask:0xf bank_mask:0xf
	v_add_f32_e32 v40, 1.0, v40
	v_add_f32_e32 v41, 1.0, v41
	v_add_f32_dpp v124, v124, v124 row_mirror row_mask:0xf bank_mask:0xf
	v_add_f32_e32 v42, 1.0, v42
	v_add_f32_e32 v43, 1.0, v43
	v_mov_b32_e32 v125, v124
	v_mov_b32_e32 v126, v124
	v_add_f32_e32 v44, 1.0, v44
	v_add_f32_e32 v45, 1.0, v45
	v_permlane16_swap_b32_e32 v125, v126
	v_add_f32_e32 v124, v125, v126
	v_mov_b32_e32 v125, v124
	v_mov_b32_e32 v126, v124
	v_add_f32_e32 v46, 1.0, v46
	v_add_f32_e32 v47, 1.0, v47
	v_permlane32_swap_b32_e32 v125, v126
	v_add_f32_e32 v124, v125, v126
	v_add_f32_e32 v48, 1.0, v48
	v_add_f32_e32 v49, 1.0, v49
	v_fmamk_f32 v124, v124, 0x3a800000, v140
	v_mul_f32_e32 v125, 0x4f800000, v124
	v_cmp_gt_f32_e32 vcc, 0xf800000, v124
	s_nop 1
	v_cndmask_b32_e32 v124, v124, v125, vcc
	v_sqrt_f32_e32 v127, v124
	s_nop 0
	v_add_u32_e32 v128, -1, v127
	v_add_u32_e32 v129, 1, v127
	v_fma_f32 v134, -v128, v127, v124
	v_fma_f32 v135, -v129, v127, v124
	v_cmp_ge_f32_e64 s[16:17], 0, v134
	v_cmp_lt_f32_e64 s[18:19], 0, v135
	s_nop 1
	v_cndmask_b32_e64 v127, v127, v128, s[16:17]
	v_cndmask_b32_e64 v127, v127, v129, s[18:19]
	v_mul_f32_e32 v125, 0x37800000, v127
	v_cndmask_b32_e32 v127, v127, v125, vcc
	v_cmp_class_f32_e32 vcc, v124, v141
	s_nop 1
	v_cndmask_b32_e32 v127, v127, v124, vcc
	v_div_scale_f32 v136, s[16:17], v127, v127, 1.0
	v_div_scale_f32 v138, vcc, 1.0, v127, 1.0
	v_rcp_f32_e32 v137, v136
	s_nop 0
	v_fma_f32 v134, -v136, v137, 1.0
	v_fmac_f32_e32 v137, v134, v137
	v_mul_f32_e32 v139, v138, v137
	v_fma_f32 v134, -v136, v139, v138
	v_fmac_f32_e32 v139, v134, v137
	v_fma_f32 v134, -v136, v139, v138
	v_div_fmas_f32 v134, v134, v137, v139
	v_div_fixup_f32 v134, v134, v127, 1.0
	v_mul_f32_e32 v2, v2, v134
	v_mul_f32_e32 v3, v3, v134
	v_mul_f32_e32 v4, v4, v134
	v_mul_f32_e32 v5, v5, v134
	v_mul_f32_e32 v6, v6, v134
	v_mul_f32_e32 v7, v7, v134
	v_mul_f32_e32 v8, v8, v134
	v_mul_f32_e32 v9, v9, v134
	v_mul_f32_e32 v10, v10, v134
	v_mul_f32_e32 v11, v11, v134
	v_mul_f32_e32 v12, v12, v134
	v_mul_f32_e32 v13, v13, v134
	v_mul_f32_e32 v14, v14, v134
	v_mul_f32_e32 v15, v15, v134
	v_mul_f32_e32 v16, v16, v134
	v_mul_f32_e32 v17, v17, v134
	v_mul_f32_e32 v2, v98, v2
	v_mul_f32_e32 v3, v99, v3
	v_mul_f32_e32 v4, v100, v4
	v_mul_f32_e32 v5, v101, v5
	v_mul_f32_e32 v6, v102, v6
	v_mul_f32_e32 v7, v103, v7
	v_mul_f32_e32 v8, v104, v8
	v_mul_f32_e32 v9, v105, v9
	v_mul_f32_e32 v10, v106, v10
	v_mul_f32_e32 v11, v107, v11
	v_mul_f32_e32 v12, v108, v12
	v_mul_f32_e32 v13, v109, v13
	v_mul_f32_e32 v14, v110, v14
	v_mul_f32_e32 v15, v111, v15
	v_mul_f32_e32 v16, v112, v16
	v_mul_f32_e32 v17, v113, v17
	v_fma_f32 v2, v2, v34, v18
	v_fma_f32 v3, v3, v35, v19
	v_fma_f32 v4, v4, v36, v20
	v_fma_f32 v5, v5, v37, v21
	v_fma_f32 v6, v6, v38, v22
	v_fma_f32 v7, v7, v39, v23
	v_fma_f32 v8, v8, v40, v24
	v_fma_f32 v9, v9, v41, v25
	v_fma_f32 v10, v10, v42, v26
	v_fma_f32 v11, v11, v43, v27
	v_fma_f32 v12, v12, v44, v28
	v_fma_f32 v13, v13, v45, v29
	v_fma_f32 v14, v14, v46, v30
	v_fma_f32 v15, v15, v47, v31
	v_fma_f32 v16, v16, v48, v32
	v_fma_f32 v17, v17, v49, v33
	v_cvt_pk_bf16_f32 v114, v2, v3
	v_cvt_pk_bf16_f32 v115, v4, v5
	v_cvt_pk_bf16_f32 v116, v6, v7
	v_cvt_pk_bf16_f32 v117, v8, v9
	v_cvt_pk_bf16_f32 v118, v10, v11
	v_cvt_pk_bf16_f32 v119, v12, v13
	v_cvt_pk_bf16_f32 v120, v14, v15
	v_cvt_pk_bf16_f32 v121, v16, v17
	s_lshl_b32 s0, s15, 11
	s_add_u32 s22, s12, s0
	s_addc_u32 s23, s13, 0
	s_cmp_ge_i32 s14, 0x8800
	s_cbranch_scc1 .Lmn7_ni_6
	s_sub_i32 s0, s14, 0x8000
	s_lshr_b32 s20, s14, 12
	s_cmp_lt_i32 s14, 0x8000
	s_cselect_b32 s0, s14, s0
	s_cselect_b32 s20, s20, 8
	s_cselect_b32 s16, s4, s6
	s_cselect_b32 s17, s5, s7
	s_lshl_b32 s0, s0, 12
	s_mul_i32 s20, s20, 0x6000
	s_add_u32 s16, s16, s0
	s_addc_u32 s17, s17, 0
	s_add_u32 s18, s8, s20
	s_addc_u32 s19, s9, 0
	global_load_dwordx4 v[2:5], v122, s[16:17] offset:0 nt
	global_load_dwordx4 v[6:9], v122, s[16:17] offset:1024 nt
	global_load_dwordx4 v[10:13], v122, s[16:17] offset:2048 nt
	global_load_dwordx4 v[14:17], v122, s[16:17] offset:3072 nt
	global_load_dwordx4 v[18:21], v122, s[18:19] offset:0
	global_load_dwordx4 v[22:25], v122, s[18:19] offset:1024
	global_load_dwordx4 v[26:29], v122, s[18:19] offset:2048
	global_load_dwordx4 v[30:33], v122, s[18:19] offset:3072
	s_add_u32 s18, s10, s20
	s_addc_u32 s19, s11, 0
	global_load_dwordx4 v[34:37], v122, s[18:19] offset:0
	global_load_dwordx4 v[38:41], v122, s[18:19] offset:1024
	global_load_dwordx4 v[42:45], v122, s[18:19] offset:2048
	global_load_dwordx4 v[46:49], v122, s[18:19] offset:3072

; DEV unsigned cvt_pk_bf16(float lo, float hi) { unsigned r; asm volatile("v_cvt_pk_bf16_f32 %0, %1, %2" : "=v"(r) : "v"(lo), "v"(hi)); return r; }
; DEV void modnorm_rows(const float* srcX, const float* srcC, int nrows, const float* g, const float* shift, const float* scale, bf16_t* dst, int gw, int NGW, int lane) {
;     for (int row0 = gw; row0 < nrows; row0 += 2 * NGW) {
;         const int row1 = row0 + NGW; const bool has1 = row1 < nrows;
;         const float* xr0 = (row0 < TX) ? srcX + (size_t)row0 * DM : srcC + (size_t)(row0 - TX) * DM;
;         const float* xr1 = !has1 ? xr0 : ((row1 < TX) ? srcX + (size_t)row1 * DM : srcC + (size_t)(row1 - TX) * DM);
;         f32x4 v0[4], v1[4]; float s0 = 0.f, s1 = 0.f;
; #pragma unroll
;         for (int j = 0; j < 4; ++j) { v0[j] = __builtin_nontemporal_load((const f32x4*)(xr0 + 256 * j + 4 * lane)); v1[j] = __builtin_nontemporal_load((const f32x4*)(xr1 + 256 * j + 4 * lane)); }
; #pragma unroll
;         for (int j = 0; j < 4; ++j) { s0 += (v0[j][0] * v0[j][0] + v0[j][1] * v0[j][1]) + (v0[j][2] * v0[j][2] + v0[j][3] * v0[j][3]); s1 += (v1[j][0] * v1[j][0] + v1[j][1] * v1[j][1]) + (v1[j][2] * v1[j][2] + v1[j][3] * v1[j][3]); }
;         const float rstd0 = 1.0f / sqrtf(wave_sum(s0) * (1.f / DM) + EPS), rstd1 = 1.0f / sqrtf(wave_sum(s1) * (1.f / DM) + EPS);
;         const int mr0 = (row0 < TX) ? (row0 >> 12) : 8, mr1 = (row1 < TX) ? (row1 >> 12) : 8;
; #pragma unroll
;         for (int j = 0; j < 4; ++j) { const int col = 256 * j + 4 * lane; const f32x4 gg = *(const f32x4*)(g + col);
;             { const f32x4 sh = *(const f32x4*)(shift + (size_t)mr0 * 6144 + col), sc = *(const f32x4*)(scale + (size_t)mr0 * 6144 + col); f32x4 y;
; #pragma unroll
;                 for (int e = 0; e < 4; ++e) y[e] = (v0[j][e] * rstd0 * gg[e]) * (1.f + sc[e]) + sh[e];
;                 u32x2 w; w.x = cvt_pk_bf16(y[0], y[1]); w.y = cvt_pk_bf16(y[2], y[3]); *(u32x2*)(dst + (size_t)row0 * DM + col) = w; }
;             if (has1) { const f32x4 sh = *(const f32x4*)(shift + (size_t)mr1 * 6144 + col), sc = *(const f32x4*)(scale + (size_t)mr1 * 6144 + col); f32x4 y;
; #pragma unroll
;                 for (int e = 0; e < 4; ++e) y[e] = (v1[j][e] * rstd1 * gg[e]) * (1.f + sc[e]) + sh[e];
;                 u32x2 w; w.x = cvt_pk_bf16(y[0], y[1]); w.y = cvt_pk_bf16(y[2], y[3]); *(u32x2*)(dst + (size_t)row1 * DM + col) = w; } }
.Lmn7_wj_8:
	v_mul_f32_e32 v114, v51, v51
	v_mul_f32_e32 v115, v53, v53
	v_mul_f32_e32 v116, v55, v55
	v_mul_f32_e32 v117, v57, v57
	v_mul_f32_e32 v118, v59, v59
	v_mul_f32_e32 v119, v61, v61
	v_mul_f32_e32 v120, v63, v63
	v_mul_f32_e32 v121, v65, v65
	v_fmac_f32_e32 v114, v50, v50
	v_fmac_f32_e32 v115, v52, v52
	v_fmac_f32_e32 v116, v54, v54
	v_fmac_f32_e32 v117, v56, v56
	v_fmac_f32_e32 v118, v58, v58
	v_fmac_f32_e32 v119, v60, v60
	v_fmac_f32_e32 v120, v62, v62
	v_fmac_f32_e32 v121, v64, v64
	v_add_f32_e32 v114, v114, v115
	v_add_f32_e32 v116, v116, v117
	v_add_f32_e32 v118, v118, v119
	v_add_f32_e32 v120, v120, v121
	v_add_f32_e32 v124, v114, v116
	v_add_f32_e32 v124, v124, v118
	v_add_f32_e32 v124, v124, v120
	v_add_f32_e32 v82, 1.0, v82
	v_add_f32_e32 v83, 1.0, v83
	v_add_f32_dpp v124, v124, v124 quad_perm:[1,0,3,2] row_mask:0xf bank_mask:0xf
	v_add_f32_e32 v84, 1.0, v84
	v_add_f32_e32 v85, 1.0, v85
	v_add_f32_dpp v124, v124, v124 quad_perm:[2,3,0,1] row_mask:0xf bank_mask:0xf
	v_add_f32_e32 v86, 1.0, v86
	v_add_f32_e32 v87, 1.0, v87
	v_add_f32_dpp v124, v124, v124 row_half_mirror row_mask:0xf bank_mask:0xf
	v_add_f32_e32 v88, 1.0, v88
	v_add_f32_e32 v89, 1.0, v89
	v_add_f32_dpp v124, v124, v124 row_mirror row_mask:0xf bank_mask:0xf
	v_add_f32_e32 v90, 1.0, v90
	v_add_f32_e32 v91, 1.0, v91
	v_mov_b32_e32 v125, v124
	v_mov_b32_e32 v126, v124
	v_add_f32_e32 v92, 1.0, v92
	v_add_f32_e32 v93, 1.0, v93
	v_permlane16_swap_b32_e32 v125, v126
	v_add_f32_e32 v124, v125, v126
	v_mov_b32_e32 v125, v124
	v_mov_b32_e32 v126, v124
	v_add_f32_e32 v94, 1.0, v94
	v_add_f32_e32 v95, 1.0, v95
	v_permlane32_swap_b32_e32 v125, v126
	v_add_f32_e32 v124, v125, v126
	v_add_f32_e32 v96, 1.0, v96
	v_add_f32_e32 v97, 1.0, v97
	v_fmamk_f32 v124, v124, 0x3a800000, v140
	v_mul_f32_e32 v125, 0x4f800000, v124
	v_cmp_gt_f32_e32 vcc, 0xf800000, v124
	s_nop 1
	v_cndmask_b32_e32 v124, v124, v125, vcc
	v_sqrt_f32_e32 v127, v124
	s_nop 0
	v_add_u32_e32 v128, -1, v127
	v_add_u32_e32 v129, 1, v127
	v_fma_f32 v134, -v128, v127, v124
	v_fma_f32 v135, -v129, v127, v124
	v_cmp_ge_f32_e64 s[16:17], 0, v134
	v_cmp_lt_f32_e64 s[18:19], 0, v135
	s_nop 1
	v_cndmask_b32_e64 v127, v127, v128, s[16:17]
	v_cndmask_b32_e64 v127, v127, v129, s[18:19]
	v_mul_f32_e32 v125, 0x37800000, v127
	v_cndmask_b32_e32 v127, v127, v125, vcc
	v_cmp_class_f32_e32 vcc, v124, v141
	s_nop 1
	v_cndmask_b32_e32 v127, v127, v124, vcc
	v_div_scale_f32 v136, s[16:17], v127, v127, 1.0
	v_div_scale_f32 v138, vcc, 1.0, v127, 1.0
	v_rcp_f32_e32 v137, v136
	s_nop 0
	v_fma_f32 v134, -v136, v137, 1.0
	v_fmac_f32_e32 v137, v134, v137
	v_mul_f32_e32 v139, v138, v137
	v_fma_f32 v134, -v136, v139, v138
	v_fmac_f32_e32 v139, v134, v137
	v_fma_f32 v134, -v136, v139, v138
	v_div_fmas_f32 v134, v134, v137, v139
	v_div_fixup_f32 v134, v134, v127, 1.0
	v_mul_f32_e32 v50, v50, v134
	v_mul_f32_e32 v51, v51, v134
	v_mul_f32_e32 v52, v52, v134
	v_mul_f32_e32 v53, v53, v134
	v_mul_f32_e32 v54, v54, v134
	v_mul_f32_e32 v55, v55, v134
	v_mul_f32_e32 v56, v56, v134
	v_mul_f32_e32 v57, v57, v134
	v_mul_f32_e32 v58, v58, v134
	v_mul_f32_e32 v59, v59, v134
	v_mul_f32_e32 v60, v60, v134
	v_mul_f32_e32 v61, v61, v134
	v_mul_f32_e32 v62, v62, v134
	v_mul_f32_e32 v63, v63, v134
	v_mul_f32_e32 v64, v64, v134
	v_mul_f32_e32 v65, v65, v134
	v_mul_f32_e32 v50, v98, v50
	v_mul_f32_e32 v51, v99, v51
	v_mul_f32_e32 v52, v100, v52
	v_mul_f32_e32 v53, v101, v53
	v_mul_f32_e32 v54, v102, v54
	v_mul_f32_e32 v55, v103, v55
	v_mul_f32_e32 v56, v104, v56
	v_mul_f32_e32 v57, v105, v57
	v_mul_f32_e32 v58, v106, v58
	v_mul_f32_e32 v59, v107, v59
	v_mul_f32_e32 v60, v108, v60
	v_mul_f32_e32 v61, v109, v61
	v_mul_f32_e32 v62, v110, v62
	v_mul_f32_e32 v63, v111, v63
	v_mul_f32_e32 v64, v112, v64
	v_mul_f32_e32 v65, v113, v65
	v_fma_f32 v50, v50, v82, v66
	v_fma_f32 v51, v51, v83, v67
	v_fma_f32 v52, v52, v84, v68
	v_fma_f32 v53, v53, v85, v69
	v_fma_f32 v54, v54, v86, v70
	v_fma_f32 v55, v55, v87, v71
	v_fma_f32 v56, v56, v88, v72
	v_fma_f32 v57, v57, v89, v73
	v_fma_f32 v58, v58, v90, v74
	v_fma_f32 v59, v59, v91, v75
	v_fma_f32 v60, v60, v92, v76
	v_fma_f32 v61, v61, v93, v77
	v_fma_f32 v62, v62, v94, v78
	v_fma_f32 v63, v63, v95, v79
	v_fma_f32 v64, v64, v96, v80
	v_fma_f32 v65, v65, v97, v81
	v_cvt_pk_bf16_f32 v114, v50, v51
	v_cvt_pk_bf16_f32 v115, v52, v53
	v_cvt_pk_bf16_f32 v116, v54, v55
	v_cvt_pk_bf16_f32 v117, v56, v57
	v_cvt_pk_bf16_f32 v118, v58, v59
	v_cvt_pk_bf16_f32 v119, v60, v61
	v_cvt_pk_bf16_f32 v120, v62, v63
	v_cvt_pk_bf16_f32 v121, v64, v65
	s_lshl_b32 s0, s15, 11
	s_add_u32 s22, s12, s0
	s_addc_u32 s23, s13, 0
	s_cmp_ge_i32 s14, 0x8800
	s_cbranch_scc1 .Lmn7_ni_9
	s_sub_i32 s0, s14, 0x8000
	s_lshr_b32 s20, s14, 12
	s_cmp_lt_i32 s14, 0x8000
	s_cselect_b32 s0, s14, s0
	s_cselect_b32 s20, s20, 8
	s_cselect_b32 s16, s4, s6
	s_cselect_b32 s17, s5, s7
	s_lshl_b32 s0, s0, 12
	s_mul_i32 s20, s20, 0x6000
	s_add_u32 s16, s16, s0
	s_addc_u32 s17, s17, 0
	s_add_u32 s18, s8, s20
	s_addc_u32 s19, s9, 0
	global_load_dwordx4 v[50:53], v122, s[16:17] offset:0 nt
	global_load_dwordx4 v[54:57], v122, s[16:17] offset:1024 nt
	global_load_dwordx4 v[58:61], v122, s[16:17] offset:2048 nt
	global_load_dwordx4 v[62:65], v122, s[16:17] offset:3072 nt
	global_load_dwordx4 v[66:69], v122, s[18:19] offset:0
	global_load_dwordx4 v[70:73], v122, s[18:19] offset:1024
	global_load_dwordx4 v[74:77], v122, s[18:19] offset:2048
	global_load_dwordx4 v[78:81], v122, s[18:19] offset:3072
	s_add_u32 s18, s10, s20
	s_addc_u32 s19, s11, 0
	global_load_dwordx4 v[82:85], v122, s[18:19] offset:0
	global_load_dwordx4 v[86:89], v122, s[18:19] offset:1024
	global_load_dwordx4 v[90:93], v122, s[18:19] offset:2048
	global_load_dwordx4 v[94:97], v122, s[18:19] offset:3072

; DEV void modnorm_rows(const float* srcX, const float* srcC, int nrows, const float* g, const float* shift, const float* scale, bf16_t* dst, int gw, int NGW, int lane) {
;     for (int row0 = gw; row0 < nrows; row0 += 2 * NGW) {
;         const int row1 = row0 + NGW; const bool has1 = row1 < nrows;
;         const float* xr0 = (row0 < TX) ? srcX + (size_t)row0 * DM : srcC + (size_t)(row0 - TX) * DM;
;         const float* xr1 = !has1 ? xr0 : ((row1 < TX) ? srcX + (size_t)row1 * DM : srcC + (size_t)(row1 - TX) * DM);
;         f32x4 v0[4], v1[4]; float s0 = 0.f, s1 = 0.f;
; #pragma unroll
;         for (int j = 0; j < 4; ++j) { v0[j] = __builtin_nontemporal_load((const f32x4*)(xr0 + 256 * j + 4 * lane)); v1[j] = __builtin_nontemporal_load((const f32x4*)(xr1 + 256 * j + 4 * lane)); }
.Lmn_phase1:
	s_waitcnt vmcnt(0) lgkmcnt(0)
	v_readlane_b32 s2, v251, 2
	v_readlane_b32 s3, v251, 3
	v_readlane_b32 s1, v251, 1
	v_readlane_b32 s14, v251, 0
	v_readlane_b32 s20, v251, 4
	v_mbcnt_lo_u32_b32 v122, -1, 0
	v_mbcnt_hi_u32_b32 v122, -1, v122
	s_load_dwordx2 s[12:13], s[2:3], 0x110
	s_load_dwordx2 s[16:17], s[2:3], 0x20
	s_lshl_b32 s1, s1, 3
	s_lshl_b32 s14, s14, 3
	s_lshr_b32 s20, s20, 6
	s_add_u32 s14, s14, s20
	s_mov_b32 s15, s14
	v_lshlrev_b32_e32 v123, 3, v122
	v_lshlrev_b32_e32 v122, 4, v122
	v_mov_b32_e32 v140, 0x358637bd
	v_mov_b32_e32 v141, 0x260
	s_waitcnt lgkmcnt(0)
	global_load_dwordx4 v[98:101], v122, s[16:17] offset:0
	global_load_dwordx4 v[102:105], v122, s[16:17] offset:1024
	global_load_dwordx4 v[106:109], v122, s[16:17] offset:2048
	global_load_dwordx4 v[110:113], v122, s[16:17] offset:3072
	s_load_dwordx2 s[4:5], s[2:3], 0x0
	s_load_dwordx2 s[6:7], s[2:3], 0x10
	s_waitcnt lgkmcnt(0)
	s_add_u32 s8, s12, 0x0
	s_addc_u32 s9, s13, 0
	s_add_u32 s10, s12, 0x1000
	s_addc_u32 s11, s13, 0
	s_add_u32 s12, s12, 0xa400000
	s_addc_u32 s13, s13, 0
	s_cmp_ge_i32 s14, 0x8800
	s_cbranch_scc1 .Lmn1_ni_2
	s_sub_i32 s0, s14, 0x8000
	s_lshr_b32 s20, s14, 12
	s_cmp_lt_i32 s14, 0x8000
	s_cselect_b32 s0, s14, s0
	s_cselect_b32 s20, s20, 8
	s_cselect_b32 s16, s4, s6
	s_cselect_b32 s17, s5, s7
	s_lshl_b32 s0, s0, 12
	s_mul_i32 s20, s20, 0x6000
	s_add_u32 s16, s16, s0
	s_addc_u32 s17, s17, 0
	s_add_u32 s18, s8, s20
	s_addc_u32 s19, s9, 0
	global_load_dwordx4 v[2:5], v122, s[16:17] offset:0 nt
	global_load_dwordx4 v[6:9], v122, s[16:17] offset:1024 nt
	global_load_dwordx4 v[10:13], v122, s[16:17] offset:2048 nt
	global_load_dwordx4 v[14:17], v122, s[16:17] offset:3072 nt
	global_load_dwordx4 v[18:21], v122, s[18:19] offset:0
	global_load_dwordx4 v[22:25], v122, s[18:19] offset:1024
	global_load_dwordx4 v[26:29], v122, s[18:19] offset:2048
	global_load_dwordx4 v[30:33], v122, s[18:19] offset:3072
	s_add_u32 s18, s10, s20
	s_addc_u32 s19, s11, 0
	global_load_dwordx4 v[34:37], v122, s[18:19] offset:0
	global_load_dwordx4 v[38:41], v122, s[18:19] offset:1024
	global_load_dwordx4 v[42:45], v122, s[18:19] offset:2048
	global_load_dwordx4 v[46:49], v122, s[18:19] offset:3072

; DEV void grid_barrier(unsigned* cnt, const unsigned target, const int tid) {
;     asm volatile("s_waitcnt vmcnt(0)" ::: "memory");
;     __syncthreads();
;     if (tid == 0) {
;         __builtin_amdgcn_fence(__ATOMIC_RELEASE, "agent");
;         __hip_atomic_fetch_add(cnt, 1u, __ATOMIC_RELAXED, __HIP_MEMORY_SCOPE_AGENT);
;         while (__hip_atomic_load(cnt, __ATOMIC_RELAXED, __HIP_MEMORY_SCOPE_AGENT) < target) __builtin_amdgcn_s_sleep(28);
;         __builtin_amdgcn_fence(__ATOMIC_ACQUIRE, "agent");
;         asm volatile("s_waitcnt vmcnt(0)" ::: "memory");
;     }
;     __syncthreads();
; }
; template <int LO, int HI>
; DEV void run_phases(LAS unsigned char* lds, const int ph_lo, const int ph_hi, const int G, const int wave0, unsigned& nbar) {
;     ...
;         if (ph + 1 < ph_hi) { __syncthreads(); if (HI == 1) cg::this_grid().sync(); else { ++nbar; grid_barrier((unsigned*)(ws + WS_BAR), nbar * (unsigned)G, tid); } }
.Lmn1_done_1:
	s_branch .LBB0_1358
.LBB0_1358:
	v_readlane_b32 s2, v251, 7
	s_add_i32 s0, s77, 1
	v_readlane_b32 s3, v251, 8
	s_cmp_ge_i32 s0, s3
	s_cbranch_scc1 .LBB0_1366
	s_barrier
	s_waitcnt vmcnt(0)
	v_readlane_b32 s0, v251, 5
	s_add_i32 s0, s0, 1
	v_cmp_eq_u32_e32 vcc, 0, v130
	v_writelane_b32 v251, s0, 5
	s_barrier
	s_and_saveexec_b64 s[0:1], vcc
	s_cbranch_execz .LBB0_1365
	v_readlane_b32 s2, v251, 2
	v_readlane_b32 s3, v251, 3
	v_readlane_b32 s4, v251, 1
	v_readlane_b32 s5, v251, 5
	s_getreg_b32 s6, hwreg(HW_REG_XCC_ID, 0, 4)
	s_load_dwordx2 s[2:3], s[2:3], 0x110
	s_lshr_b32 s4, s4, 3
	s_mul_i32 s4, s4, s5
	s_lshl_b32 s7, s5, 3
	s_lshl_b32 s6, s6, 2
	s_add_u32 s6, s6, 0x40
	v_mov_b32_e32 v3, 1
	v_mov_b32_e32 v2, s6
	v_mov_b32_e32 v5, 0
	s_waitcnt lgkmcnt(0)
	s_add_u32 s2, s2, 0x300000
	s_addc_u32 s3, s3, 0
	global_atomic_add v4, v2, v3, s[2:3] sc0
	s_waitcnt vmcnt(0)
	v_add_u32_e32 v4, 1, v4
	v_cmp_eq_u32_e32 vcc, s4, v4
	s_cbranch_vccz .Lgb2_follow
	buffer_wbl2 sc1
	s_waitcnt vmcnt(0)
	global_atomic_add v5, v3, s[2:3]
